# speedup vs baseline: 1.0380x; 1.0079x over previous
.LBB0_457:
	v_mov_b32_e32 v156, v194
	v_mov_b32_e32 v157, v165
	v_mov_b32_e32 v158, v195
	v_mov_b32_e32 v159, v193
	v_lshlrev_b32_e32 v202, 16, v142
	v_lshlrev_b32_e32 v144, 4, v158
	v_lshl_add_u32 v144, v159, 2, v144
	v_ashrrev_i32_e32 v145, 31, v144
	v_lshlrev_b64 v[148:149], 2, v[144:145]
	v_lshl_add_u64 v[152:153], s[66:67], 0, v[148:149]
	v_lshl_add_u64 v[154:155], s[64:65], 0, v[148:149]
	global_load_dwordx4 v[144:147], v[152:153], off
	global_load_dwordx4 v[148:151], v[154:155], off
	v_and_b32_e32 v246, 63, v163
	v_lshlrev_b32_e32 v246, 2, v246
	global_load_dword v247, v246, s[68:69] offset:256
	global_load_dword v246, v246, s[68:69]
	v_and_b32_e32 v203, 0xffff0000, v142
	v_lshlrev_b32_e32 v142, 6, v158
	v_lshl_add_u32 v158, v158, 2, v159
	v_lshlrev_b32_e32 v160, 15, v156
	v_lshl_add_u32 v142, v156, 8, v142
	v_xor_b32_e32 v156, v158, v157
	v_lshl_or_b32 v201, v159, 4, v142
	v_lshlrev_b32_e32 v142, 4, v156
	v_lshlrev_b32_e32 v198, 8, v157
	v_add3_u32 v142, v142, v160, s89
	v_add_u32_e32 v158, v142, v198
	v_lshlrev_b32_e32 v196, 16, v140
	v_and_b32_e32 v197, 0xffff0000, v140
	v_lshlrev_b32_e32 v140, 16, v141
	v_and_b32_e32 v141, 0xffff0000, v141
	v_or_b32_e32 v156, v201, v157
	s_movk_i32 s4, 0x100
	v_add_u32_e32 v200, 0x100, v156
	v_cmp_gt_i32_e64 s[4:5], s4, v156
	s_and_b32 s9, s9, 0xffff
	v_cmp_lt_i32_e32 vcc, s81, v156
	s_waitcnt vmcnt(0)
	v_add_f32_e32 v142, v124, v144
	v_add_f32_e32 v159, v120, v148
	v_add_f32_e32 v160, v125, v145
	v_add_f32_e32 v198, v121, v149
	v_add_f32_e32 v199, v126, v146
	v_add_f32_e32 v204, v122, v150
	v_add_f32_e32 v205, v127, v147
	v_add_f32_e32 v206, v123, v151
	v_med3_f32 v142, v142, s6, v191
	v_med3_f32 v159, v159, s6, v191
	v_med3_f32 v160, v160, s6, v191
	v_med3_f32 v198, v198, s6, v191
	v_med3_f32 v199, v199, s6, v191
	v_med3_f32 v204, v204, s6, v191
	v_med3_f32 v205, v205, s6, v191
	v_med3_f32 v206, v206, s6, v191
	v_mul_f32_e32 v142, 0xbfb8aa3b, v142
	v_mul_f32_e32 v159, 0xbfb8aa3b, v159
	v_mul_f32_e32 v160, 0xbfb8aa3b, v160
	v_mul_f32_e32 v207, 0xbfb8aa3b, v198
	v_mul_f32_e32 v208, 0xbfb8aa3b, v199
	v_mul_f32_e32 v209, 0xbfb8aa3b, v204
	v_mul_f32_e32 v205, 0xbfb8aa3b, v205
	v_mul_f32_e32 v206, 0xbfb8aa3b, v206
	v_exp_f32_e32 v198, v142
	v_exp_f32_e32 v142, v159
	v_exp_f32_e32 v199, v160
	v_exp_f32_e32 v159, v207
	v_exp_f32_e32 v204, v208
	v_exp_f32_e32 v160, v209
	v_exp_f32_e32 v205, v205
	v_exp_f32_e32 v206, v206
	v_add_f32_e32 v142, 1.0, v142
	v_add_f32_e32 v159, 1.0, v159
	v_pk_add_f32 v[198:199], v[198:199], 1.0 op_sel_hi:[1,0]
	v_add_f32_e32 v160, 1.0, v160
	v_add_f32_e32 v211, 1.0, v206
	v_pk_add_f32 v[204:205], v[204:205], 1.0 op_sel_hi:[1,0]
	v_mul_f32_e32 v206, v198, v142
	v_mul_f32_e32 v207, v199, v159
	v_mul_f32_e32 v208, v204, v160
	v_mul_f32_e32 v209, v205, v211
	v_rcp_f32_e32 v206, v206
	v_rcp_f32_e32 v207, v207
	v_rcp_f32_e32 v208, v208
	v_rcp_f32_e32 v209, v209
	v_mul_f32_e32 v142, v142, v206
	v_pk_mul_f32 v[198:199], v[198:199], v[206:207]
	v_mul_f32_e32 v160, v160, v208
	v_pk_mul_f32 v[204:205], v[204:205], v[208:209]
	v_mul_f32_e32 v206, v211, v209
	v_pk_mul_f32 v[196:197], v[198:199], v[196:197]
	v_mul_f32_e32 v160, 0x437f0000, v160
	v_pk_mul_f32 v[140:141], v[204:205], v[140:141]
	v_mul_f32_e32 v198, 0x437f0000, v206
	v_rndne_f32_e32 v160, v160
	v_cvt_pk_f16_f32 v140, v140, v141
	v_rndne_f32_e32 v141, v198
	v_min_f32_e32 v160, 0x437f0000, v160
	v_min_f32_e32 v141, 0x437f0000, v141
	v_cvt_f16_f32_e32 v141, v141
	v_cvt_f16_f32_e32 v160, v160
	v_mul_f32_e32 v159, v159, v207
	v_mul_f32_e32 v159, 0x437f0000, v159
	v_bfi_b32 v199, s98, v141, v140
	v_pack_b32_f16 v198, v160, v140
	v_add_f32_e32 v140, v104, v148
	v_rndne_f32_e32 v159, v159
	v_med3_f32 v140, v140, s6, v191
	v_min_f32_e32 v159, 0x437f0000, v159
	v_mul_f32_e32 v140, 0xbfb8aa3b, v140
	v_cvt_f16_f32_e32 v159, v159
	v_exp_f32_e32 v141, v140
	v_mul_f32_e32 v142, 0x437f0000, v142
	v_rndne_f32_e32 v142, v142
	v_cvt_pk_f16_f32 v196, v196, v197
	v_add_f32_e32 v210, v108, v144
	v_min_f32_e32 v142, 0x437f0000, v142
	v_bfi_b32 v197, s98, v159, v196
	v_add_f32_e32 v159, 1.0, v141
	v_add_f32_e32 v141, v109, v145
	v_cvt_f16_f32_e32 v142, v142
	v_med3_f32 v140, v210, s6, v191
	v_med3_f32 v141, v141, s6, v191
	v_mul_f32_e32 v140, 0xbfb8aa3b, v140
	v_mul_f32_e32 v141, 0xbfb8aa3b, v141
	v_exp_f32_e32 v140, v140
	v_exp_f32_e32 v141, v141
	v_pack_b32_f16 v196, v142, v196
	v_add_f32_e32 v142, v105, v149
	v_med3_f32 v142, v142, s6, v191
	v_mul_f32_e32 v142, 0xbfb8aa3b, v142
	v_pk_add_f32 v[140:141], v[140:141], 1.0 op_sel_hi:[1,0]
	v_exp_f32_e32 v160, v142
	v_mul_f32_e32 v142, v140, v159
	v_rcp_f32_e32 v142, v142
	ds_write_b128 v158, v[196:199]
	v_lshlrev_b32_e32 v196, 16, v143
	v_and_b32_e32 v197, 0xffff0000, v143
	v_add_f32_e32 v160, 1.0, v160
	v_mul_f32_e32 v143, v159, v142
	v_mul_f32_e32 v159, 0x437f0000, v143
	v_mul_f32_e32 v143, v141, v160
	v_rcp_f32_e32 v143, v143
	v_rndne_f32_e32 v159, v159
	v_min_f32_e32 v159, 0x437f0000, v159
	v_cvt_f16_f32_e32 v159, v159
	v_pk_mul_f32 v[140:141], v[140:141], v[142:143]
	v_add_f32_e32 v142, v107, v151
	v_pk_mul_f32 v[140:141], v[140:141], v[202:203]
	v_med3_f32 v142, v142, s6, v191
	v_cvt_pk_f16_f32 v198, v140, v141
	v_add_f32_e32 v141, v106, v150
	v_med3_f32 v141, v141, s6, v191
	v_mul_f32_e32 v141, 0xbfb8aa3b, v141
	v_exp_f32_e32 v141, v141
	v_mul_f32_e32 v140, v160, v143
	v_mul_f32_e32 v140, 0x437f0000, v140
	v_rndne_f32_e32 v143, v140
	v_add_f32_e32 v140, v110, v146
	v_add_f32_e32 v160, 1.0, v141
	v_add_f32_e32 v141, v111, v147
	v_med3_f32 v140, v140, s6, v191
	v_med3_f32 v141, v141, s6, v191
	v_mul_f32_e32 v140, 0xbfb8aa3b, v140
	v_mul_f32_e32 v141, 0xbfb8aa3b, v141
	v_exp_f32_e32 v140, v140
	v_exp_f32_e32 v141, v141
	v_mul_f32_e32 v142, 0xbfb8aa3b, v142
	v_exp_f32_e32 v199, v142
	v_min_f32_e32 v143, 0x437f0000, v143
	v_pk_add_f32 v[140:141], v[140:141], 1.0 op_sel_hi:[1,0]
	v_cvt_f16_f32_e32 v202, v143
	v_mul_f32_e32 v142, v140, v160
	v_rcp_f32_e32 v142, v142
	v_add_f32_e32 v199, 1.0, v199
	v_mul_f32_e32 v143, v160, v142
	v_mul_f32_e32 v160, 0x437f0000, v143
	v_mul_f32_e32 v143, v141, v199
	v_rcp_f32_e32 v143, v143
	v_rndne_f32_e32 v160, v160
	v_min_f32_e32 v160, 0x437f0000, v160
	v_cvt_f16_f32_e32 v160, v160
	v_mul_f32_e32 v199, v199, v143
	v_mul_f32_e32 v199, 0x437f0000, v199
	v_rndne_f32_e32 v199, v199
	v_min_f32_e32 v199, 0x437f0000, v199
	v_cvt_f16_f32_e32 v199, v199
	v_pk_mul_f32 v[140:141], v[140:141], v[142:143]
	s_nop 0
	v_pk_mul_f32 v[140:141], v[140:141], v[196:197]
	v_lshlrev_b32_e32 v196, 16, v137
	v_cvt_pk_f16_f32 v140, v140, v141
	v_bfi_b32 v143, s98, v199, v140
	v_bfi_b32 v141, s98, v202, v198
	v_pack_b32_f16 v142, v160, v140
	v_pack_b32_f16 v140, v159, v198
	ds_write_b128 v158, v[140:143] offset:4096
	v_add_f32_e32 v142, v88, v148
	v_lshlrev_b32_e32 v140, 16, v136
	v_and_b32_e32 v141, 0xffff0000, v136
	v_add_f32_e32 v136, v92, v144
	v_med3_f32 v142, v142, s6, v191
	v_mul_f32_e32 v142, 0xbfb8aa3b, v142
	v_med3_f32 v136, v136, s6, v191
	v_exp_f32_e32 v143, v142
	v_mul_f32_e32 v136, 0xbfb8aa3b, v136
	v_exp_f32_e32 v142, v136
	v_add_f32_e32 v136, v93, v145
	v_med3_f32 v136, v136, s6, v191
	v_mul_f32_e32 v136, 0xbfb8aa3b, v136
	v_add_f32_e32 v159, 1.0, v143
	v_exp_f32_e32 v143, v136
	v_add_f32_e32 v160, v89, v149
	v_med3_f32 v136, v160, s6, v191
	v_mul_f32_e32 v136, 0xbfb8aa3b, v136
	v_pk_add_f32 v[142:143], v[142:143], 1.0 op_sel_hi:[1,0]
	v_exp_f32_e32 v160, v136
	v_mul_f32_e32 v136, v142, v159
	v_rcp_f32_e32 v136, v136
	v_and_b32_e32 v197, 0xffff0000, v137
	v_add_f32_e32 v160, 1.0, v160
	v_mul_f32_e32 v137, v159, v136
	v_mul_f32_e32 v159, 0x437f0000, v137
	v_mul_f32_e32 v137, v143, v160
	v_rcp_f32_e32 v137, v137
	v_rndne_f32_e32 v159, v159
	v_min_f32_e32 v159, 0x437f0000, v159
	v_cvt_f16_f32_e32 v159, v159
	v_pk_mul_f32 v[142:143], v[142:143], v[136:137]
	v_mul_f32_e32 v136, v160, v137
	v_add_f32_e32 v137, v90, v150
	v_med3_f32 v137, v137, s6, v191
	v_mul_f32_e32 v137, 0xbfb8aa3b, v137
	v_exp_f32_e32 v137, v137
	v_pk_mul_f32 v[140:141], v[142:143], v[140:141]
	v_mul_f32_e32 v136, 0x437f0000, v136
	v_cvt_pk_f16_f32 v198, v140, v141
	v_rndne_f32_e32 v141, v136
	v_add_f32_e32 v136, v94, v146
	v_add_f32_e32 v142, 1.0, v137
	v_add_f32_e32 v137, v95, v147
	v_med3_f32 v136, v136, s6, v191
	v_med3_f32 v137, v137, s6, v191
	v_mul_f32_e32 v136, 0xbfb8aa3b, v136
	v_mul_f32_e32 v137, 0xbfb8aa3b, v137
	v_exp_f32_e32 v136, v136
	v_exp_f32_e32 v137, v137
	v_add_f32_e32 v140, v91, v151
	v_med3_f32 v140, v140, s6, v191
	v_mul_f32_e32 v140, 0xbfb8aa3b, v140
	v_pk_add_f32 v[136:137], v[136:137], 1.0 op_sel_hi:[1,0]
	v_exp_f32_e32 v143, v140
	v_mul_f32_e32 v140, v136, v142
	v_rcp_f32_e32 v140, v140
	v_min_f32_e32 v141, 0x437f0000, v141
	v_cvt_f16_f32_e32 v160, v141
	v_add_f32_e32 v143, 1.0, v143
	v_mul_f32_e32 v141, v142, v140
	v_mul_f32_e32 v142, 0x437f0000, v141
	v_mul_f32_e32 v141, v137, v143
	v_rcp_f32_e32 v141, v141
	v_rndne_f32_e32 v142, v142
	v_min_f32_e32 v142, 0x437f0000, v142
	v_cvt_f16_f32_e32 v142, v142
	v_mul_f32_e32 v143, v143, v141
	v_mul_f32_e32 v143, 0x437f0000, v143
	v_rndne_f32_e32 v143, v143
	v_min_f32_e32 v143, 0x437f0000, v143
	v_cvt_f16_f32_e32 v143, v143
	v_pk_mul_f32 v[136:137], v[136:137], v[140:141]
	v_bfi_b32 v141, s98, v160, v198
	v_pk_mul_f32 v[136:137], v[136:137], v[196:197]
	v_pack_b32_f16 v140, v159, v198
	v_cvt_pk_f16_f32 v136, v136, v137
	v_bfi_b32 v143, s98, v143, v136
	v_pack_b32_f16 v142, v142, v136
	ds_write_b128 v158, v[140:143] offset:8192
	v_add_f32_e32 v140, v72, v148
	v_lshlrev_b32_e32 v136, 16, v138
	v_and_b32_e32 v137, 0xffff0000, v138
	v_add_f32_e32 v138, v76, v144
	v_med3_f32 v140, v140, s6, v191
	v_mul_f32_e32 v140, 0xbfb8aa3b, v140
	v_med3_f32 v138, v138, s6, v191
	v_exp_f32_e32 v141, v140
	v_mul_f32_e32 v138, 0xbfb8aa3b, v138
	v_exp_f32_e32 v140, v138
	v_add_f32_e32 v138, v77, v145
	v_med3_f32 v138, v138, s6, v191
	v_mul_f32_e32 v138, 0xbfb8aa3b, v138
	v_add_f32_e32 v159, 1.0, v141
	v_exp_f32_e32 v141, v138
	v_add_f32_e32 v142, v73, v149
	v_med3_f32 v138, v142, s6, v191
	v_mul_f32_e32 v138, 0xbfb8aa3b, v138
	v_pk_add_f32 v[140:141], v[140:141], 1.0 op_sel_hi:[1,0]
	v_exp_f32_e32 v160, v138
	v_mul_f32_e32 v138, v140, v159
	v_rcp_f32_e32 v138, v138
	v_lshlrev_b32_e32 v142, 16, v139
	v_and_b32_e32 v143, 0xffff0000, v139
	v_add_f32_e32 v160, 1.0, v160
	v_mul_f32_e32 v139, v159, v138
	v_mul_f32_e32 v159, 0x437f0000, v139
	v_mul_f32_e32 v139, v141, v160
	v_rcp_f32_e32 v139, v139
	v_rndne_f32_e32 v159, v159
	v_min_f32_e32 v159, 0x437f0000, v159
	v_cvt_f16_f32_e32 v159, v159
	v_pk_mul_f32 v[140:141], v[140:141], v[138:139]
	v_add_f32_e32 v138, v75, v151
	v_pk_mul_f32 v[136:137], v[140:141], v[136:137]
	v_med3_f32 v138, v138, s6, v191
	v_cvt_pk_f16_f32 v140, v136, v137
	v_add_f32_e32 v137, v74, v150
	v_med3_f32 v137, v137, s6, v191
	v_mul_f32_e32 v137, 0xbfb8aa3b, v137
	v_exp_f32_e32 v137, v137
	v_mul_f32_e32 v136, v160, v139
	v_mul_f32_e32 v136, 0x437f0000, v136
	v_rndne_f32_e32 v139, v136
	v_add_f32_e32 v136, v78, v146
	v_add_f32_e32 v141, 1.0, v137
	v_add_f32_e32 v137, v79, v147
	v_med3_f32 v136, v136, s6, v191
	v_med3_f32 v137, v137, s6, v191
	v_mul_f32_e32 v136, 0xbfb8aa3b, v136
	v_mul_f32_e32 v137, 0xbfb8aa3b, v137
	v_exp_f32_e32 v136, v136
	v_exp_f32_e32 v137, v137
	v_mul_f32_e32 v138, 0xbfb8aa3b, v138
	v_exp_f32_e32 v160, v138
	v_min_f32_e32 v139, 0x437f0000, v139
	v_pk_add_f32 v[136:137], v[136:137], 1.0 op_sel_hi:[1,0]
	v_cvt_f16_f32_e32 v196, v139
	v_mul_f32_e32 v138, v136, v141
	v_rcp_f32_e32 v138, v138
	v_add_f32_e32 v160, 1.0, v160
	v_mul_f32_e32 v139, v141, v138
	v_mul_f32_e32 v141, 0x437f0000, v139
	v_mul_f32_e32 v139, v137, v160
	v_rcp_f32_e32 v139, v139
	v_rndne_f32_e32 v141, v141
	v_min_f32_e32 v141, 0x437f0000, v141
	v_cvt_f16_f32_e32 v141, v141
	v_mul_f32_e32 v160, v160, v139
	v_mul_f32_e32 v160, 0x437f0000, v160
	v_rndne_f32_e32 v160, v160
	v_min_f32_e32 v160, 0x437f0000, v160
	v_cvt_f16_f32_e32 v160, v160
	v_pk_mul_f32 v[136:137], v[136:137], v[138:139]
	s_nop 0
	v_pk_mul_f32 v[136:137], v[136:137], v[142:143]
	s_nop 0
	v_cvt_pk_f16_f32 v136, v136, v137
	v_bfi_b32 v139, s98, v160, v136
	v_bfi_b32 v137, s98, v196, v140
	v_pack_b32_f16 v138, v141, v136
	v_pack_b32_f16 v136, v159, v140
	ds_write_b128 v158, v[136:139] offset:12288
	v_add_f32_e32 v138, v56, v148
	v_lshlrev_b32_e32 v136, 16, v132
	v_and_b32_e32 v137, 0xffff0000, v132
	v_add_f32_e32 v132, v60, v144
	v_med3_f32 v138, v138, s6, v191
	v_mul_f32_e32 v138, 0xbfb8aa3b, v138
	v_med3_f32 v132, v132, s6, v191
	v_exp_f32_e32 v139, v138
	v_mul_f32_e32 v132, 0xbfb8aa3b, v132
	v_exp_f32_e32 v138, v132
	v_add_f32_e32 v132, v61, v145
	v_med3_f32 v132, v132, s6, v191
	v_mul_f32_e32 v132, 0xbfb8aa3b, v132
	v_add_f32_e32 v142, 1.0, v139
	v_exp_f32_e32 v139, v132
	v_add_f32_e32 v140, v57, v149
	v_med3_f32 v132, v140, s6, v191
	v_mul_f32_e32 v132, 0xbfb8aa3b, v132
	v_pk_add_f32 v[138:139], v[138:139], 1.0 op_sel_hi:[1,0]
	v_exp_f32_e32 v143, v132
	v_mul_f32_e32 v132, v138, v142
	v_rcp_f32_e32 v132, v132
	v_lshlrev_b32_e32 v140, 16, v133
	v_and_b32_e32 v141, 0xffff0000, v133
	v_add_f32_e32 v143, 1.0, v143
	v_mul_f32_e32 v133, v142, v132
	v_mul_f32_e32 v142, 0x437f0000, v133
	v_mul_f32_e32 v133, v139, v143
	v_rcp_f32_e32 v133, v133
	v_rndne_f32_e32 v142, v142
	v_min_f32_e32 v142, 0x437f0000, v142
	v_cvt_f16_f32_e32 v142, v142
	v_pk_mul_f32 v[138:139], v[138:139], v[132:133]
	v_mul_f32_e32 v132, v143, v133
	v_add_f32_e32 v133, v58, v150
	v_med3_f32 v133, v133, s6, v191
	v_mul_f32_e32 v133, 0xbfb8aa3b, v133
	v_exp_f32_e32 v133, v133
	v_pk_mul_f32 v[136:137], v[138:139], v[136:137]
	v_mul_f32_e32 v132, 0x437f0000, v132
	v_cvt_pk_f16_f32 v159, v136, v137
	v_rndne_f32_e32 v137, v132
	v_add_f32_e32 v132, v62, v146
	v_add_f32_e32 v138, 1.0, v133
	v_add_f32_e32 v133, v63, v147
	v_med3_f32 v132, v132, s6, v191
	v_med3_f32 v133, v133, s6, v191
	v_mul_f32_e32 v132, 0xbfb8aa3b, v132
	v_mul_f32_e32 v133, 0xbfb8aa3b, v133
	v_exp_f32_e32 v132, v132
	v_exp_f32_e32 v133, v133
	v_add_f32_e32 v136, v59, v151
	v_med3_f32 v136, v136, s6, v191
	v_mul_f32_e32 v136, 0xbfb8aa3b, v136
	v_pk_add_f32 v[132:133], v[132:133], 1.0 op_sel_hi:[1,0]
	v_exp_f32_e32 v139, v136
	v_mul_f32_e32 v136, v132, v138
	v_rcp_f32_e32 v136, v136
	v_min_f32_e32 v137, 0x437f0000, v137
	v_cvt_f16_f32_e32 v143, v137
	v_add_f32_e32 v139, 1.0, v139
	v_mul_f32_e32 v137, v138, v136
	v_mul_f32_e32 v138, 0x437f0000, v137
	v_mul_f32_e32 v137, v133, v139
	v_rcp_f32_e32 v137, v137
	v_rndne_f32_e32 v138, v138
	v_min_f32_e32 v138, 0x437f0000, v138
	v_cvt_f16_f32_e32 v138, v138
	v_mul_f32_e32 v139, v139, v137
	v_mul_f32_e32 v139, 0x437f0000, v139
	v_rndne_f32_e32 v139, v139
	v_min_f32_e32 v139, 0x437f0000, v139
	v_cvt_f16_f32_e32 v139, v139
	v_pk_mul_f32 v[132:133], v[132:133], v[136:137]
	v_bfi_b32 v137, s98, v143, v159
	v_pk_mul_f32 v[132:133], v[132:133], v[140:141]
	v_pack_b32_f16 v136, v142, v159
	v_cvt_pk_f16_f32 v132, v132, v133
	v_bfi_b32 v139, s98, v139, v132
	v_pack_b32_f16 v138, v138, v132
	ds_write_b128 v158, v[136:139] offset:16384
	v_add_f32_e32 v136, v40, v148
	v_lshlrev_b32_e32 v132, 16, v134
	v_and_b32_e32 v133, 0xffff0000, v134
	v_add_f32_e32 v134, v44, v144
	v_med3_f32 v136, v136, s6, v191
	v_mul_f32_e32 v136, 0xbfb8aa3b, v136
	v_med3_f32 v134, v134, s6, v191
	v_exp_f32_e32 v137, v136
	v_mul_f32_e32 v134, 0xbfb8aa3b, v134
	v_exp_f32_e32 v136, v134
	v_add_f32_e32 v134, v45, v145
	v_med3_f32 v134, v134, s6, v191
	v_mul_f32_e32 v134, 0xbfb8aa3b, v134
	v_add_f32_e32 v140, 1.0, v137
	v_exp_f32_e32 v137, v134
	v_add_f32_e32 v138, v41, v149
	v_med3_f32 v134, v138, s6, v191
	v_mul_f32_e32 v134, 0xbfb8aa3b, v134
	v_pk_add_f32 v[136:137], v[136:137], 1.0 op_sel_hi:[1,0]
	v_exp_f32_e32 v141, v134
	v_mul_f32_e32 v134, v136, v140
	v_rcp_f32_e32 v134, v134
	v_lshlrev_b32_e32 v138, 16, v135
	v_and_b32_e32 v139, 0xffff0000, v135
	v_add_f32_e32 v141, 1.0, v141
	v_mul_f32_e32 v135, v140, v134
	v_mul_f32_e32 v140, 0x437f0000, v135
	v_mul_f32_e32 v135, v137, v141
	v_rcp_f32_e32 v135, v135
	v_rndne_f32_e32 v140, v140
	v_min_f32_e32 v140, 0x437f0000, v140
	v_cvt_f16_f32_e32 v140, v140
	v_pk_mul_f32 v[136:137], v[136:137], v[134:135]
	v_add_f32_e32 v134, v43, v151
	v_pk_mul_f32 v[132:133], v[136:137], v[132:133]
	v_med3_f32 v134, v134, s6, v191
	v_cvt_pk_f16_f32 v136, v132, v133
	v_add_f32_e32 v133, v42, v150
	v_med3_f32 v133, v133, s6, v191
	v_mul_f32_e32 v133, 0xbfb8aa3b, v133
	v_exp_f32_e32 v133, v133
	v_mul_f32_e32 v132, v141, v135
	v_mul_f32_e32 v132, 0x437f0000, v132
	v_rndne_f32_e32 v135, v132
	v_add_f32_e32 v132, v46, v146
	v_add_f32_e32 v137, 1.0, v133
	v_add_f32_e32 v133, v47, v147
	v_med3_f32 v132, v132, s6, v191
	v_med3_f32 v133, v133, s6, v191
	v_mul_f32_e32 v132, 0xbfb8aa3b, v132
	v_mul_f32_e32 v133, 0xbfb8aa3b, v133
	v_exp_f32_e32 v132, v132
	v_exp_f32_e32 v133, v133
	v_mul_f32_e32 v134, 0xbfb8aa3b, v134
	v_exp_f32_e32 v141, v134
	v_min_f32_e32 v135, 0x437f0000, v135
	v_pk_add_f32 v[132:133], v[132:133], 1.0 op_sel_hi:[1,0]
	v_cvt_f16_f32_e32 v142, v135
	v_mul_f32_e32 v134, v132, v137
	v_rcp_f32_e32 v134, v134
	v_add_f32_e32 v141, 1.0, v141
	v_mul_f32_e32 v135, v137, v134
	v_mul_f32_e32 v137, 0x437f0000, v135
	v_mul_f32_e32 v135, v133, v141
	v_rcp_f32_e32 v135, v135
	v_rndne_f32_e32 v137, v137
	v_min_f32_e32 v137, 0x437f0000, v137
	v_cvt_f16_f32_e32 v137, v137
	v_mul_f32_e32 v141, v141, v135
	v_mul_f32_e32 v141, 0x437f0000, v141
	v_rndne_f32_e32 v141, v141
	v_min_f32_e32 v141, 0x437f0000, v141
	v_cvt_f16_f32_e32 v141, v141
	v_pk_mul_f32 v[132:133], v[132:133], v[134:135]
	s_nop 0
	v_pk_mul_f32 v[132:133], v[132:133], v[138:139]
	s_nop 0
	v_cvt_pk_f16_f32 v132, v132, v133
	v_bfi_b32 v135, s98, v141, v132
	v_bfi_b32 v133, s98, v142, v136
	v_pack_b32_f16 v134, v137, v132
	v_pack_b32_f16 v132, v140, v136
	ds_write_b128 v158, v[132:135] offset:20480
	v_add_f32_e32 v134, v24, v148
	v_lshlrev_b32_e32 v132, 16, v128
	v_and_b32_e32 v133, 0xffff0000, v128
	v_add_f32_e32 v128, v28, v144
	v_med3_f32 v134, v134, s6, v191
	v_mul_f32_e32 v134, 0xbfb8aa3b, v134
	v_med3_f32 v128, v128, s6, v191
	v_exp_f32_e32 v135, v134
	v_mul_f32_e32 v128, 0xbfb8aa3b, v128
	v_exp_f32_e32 v134, v128
	v_add_f32_e32 v128, v29, v145
	v_med3_f32 v128, v128, s6, v191
	v_mul_f32_e32 v128, 0xbfb8aa3b, v128
	v_add_f32_e32 v138, 1.0, v135
	v_exp_f32_e32 v135, v128
	v_add_f32_e32 v136, v25, v149
	v_med3_f32 v128, v136, s6, v191
	v_mul_f32_e32 v128, 0xbfb8aa3b, v128
	v_pk_add_f32 v[134:135], v[134:135], 1.0 op_sel_hi:[1,0]
	v_exp_f32_e32 v139, v128
	v_mul_f32_e32 v128, v134, v138
	v_rcp_f32_e32 v128, v128
	v_lshlrev_b32_e32 v136, 16, v129
	v_and_b32_e32 v137, 0xffff0000, v129
	v_add_f32_e32 v139, 1.0, v139
	v_mul_f32_e32 v129, v138, v128
	v_mul_f32_e32 v138, 0x437f0000, v129
	v_mul_f32_e32 v129, v135, v139
	v_rcp_f32_e32 v129, v129
	v_rndne_f32_e32 v138, v138
	v_min_f32_e32 v138, 0x437f0000, v138
	v_cvt_f16_f32_e32 v138, v138
	v_pk_mul_f32 v[134:135], v[134:135], v[128:129]
	v_mul_f32_e32 v128, v139, v129
	v_add_f32_e32 v129, v26, v150
	v_med3_f32 v129, v129, s6, v191
	v_mul_f32_e32 v129, 0xbfb8aa3b, v129
	v_exp_f32_e32 v129, v129
	v_pk_mul_f32 v[132:133], v[134:135], v[132:133]
	v_mul_f32_e32 v128, 0x437f0000, v128
	v_cvt_pk_f16_f32 v140, v132, v133
	v_rndne_f32_e32 v133, v128
	v_add_f32_e32 v128, v30, v146
	v_add_f32_e32 v134, 1.0, v129
	v_add_f32_e32 v129, v31, v147
	v_med3_f32 v128, v128, s6, v191
	v_med3_f32 v129, v129, s6, v191
	v_mul_f32_e32 v128, 0xbfb8aa3b, v128
	v_mul_f32_e32 v129, 0xbfb8aa3b, v129
	v_exp_f32_e32 v128, v128
	v_exp_f32_e32 v129, v129
	v_add_f32_e32 v132, v27, v151
	v_med3_f32 v132, v132, s6, v191
	v_mul_f32_e32 v132, 0xbfb8aa3b, v132
	v_pk_add_f32 v[128:129], v[128:129], 1.0 op_sel_hi:[1,0]
	v_exp_f32_e32 v135, v132
	v_mul_f32_e32 v132, v128, v134
	v_rcp_f32_e32 v132, v132
	v_min_f32_e32 v133, 0x437f0000, v133
	v_cvt_f16_f32_e32 v139, v133
	v_add_f32_e32 v135, 1.0, v135
	v_mul_f32_e32 v133, v134, v132
	v_mul_f32_e32 v134, 0x437f0000, v133
	v_mul_f32_e32 v133, v129, v135
	v_rcp_f32_e32 v133, v133
	v_rndne_f32_e32 v134, v134
	v_min_f32_e32 v134, 0x437f0000, v134
	v_cvt_f16_f32_e32 v134, v134
	v_mul_f32_e32 v135, v135, v133
	v_mul_f32_e32 v135, 0x437f0000, v135
	v_rndne_f32_e32 v135, v135
	v_min_f32_e32 v135, 0x437f0000, v135
	v_cvt_f16_f32_e32 v135, v135
	v_pk_mul_f32 v[128:129], v[128:129], v[132:133]
	v_bfi_b32 v133, s98, v139, v140
	v_pk_mul_f32 v[128:129], v[128:129], v[136:137]
	v_pack_b32_f16 v132, v138, v140
	v_cvt_pk_f16_f32 v128, v128, v129
	v_bfi_b32 v135, s98, v135, v128
	v_pack_b32_f16 v134, v134, v128
	ds_write_b128 v158, v[132:135] offset:24576
	v_add_f32_e32 v132, v8, v148
	v_lshlrev_b32_e32 v128, 16, v130
	v_and_b32_e32 v129, 0xffff0000, v130
	v_add_f32_e32 v130, v12, v144
	v_med3_f32 v132, v132, s6, v191
	v_mul_f32_e32 v132, 0xbfb8aa3b, v132
	v_med3_f32 v130, v130, s6, v191
	v_exp_f32_e32 v133, v132
	v_mul_f32_e32 v130, 0xbfb8aa3b, v130
	v_exp_f32_e32 v132, v130
	v_add_f32_e32 v130, v13, v145
	v_med3_f32 v130, v130, s6, v191
	v_mul_f32_e32 v130, 0xbfb8aa3b, v130
	v_add_f32_e32 v136, 1.0, v133
	v_exp_f32_e32 v133, v130
	v_add_f32_e32 v134, v9, v149
	v_med3_f32 v130, v134, s6, v191
	v_mul_f32_e32 v130, 0xbfb8aa3b, v130
	v_pk_add_f32 v[132:133], v[132:133], 1.0 op_sel_hi:[1,0]
	v_exp_f32_e32 v137, v130
	v_mul_f32_e32 v130, v132, v136
	v_rcp_f32_e32 v130, v130
	v_lshlrev_b32_e32 v134, 16, v131
	v_and_b32_e32 v135, 0xffff0000, v131
	v_add_f32_e32 v137, 1.0, v137
	v_mul_f32_e32 v131, v136, v130
	v_mul_f32_e32 v136, 0x437f0000, v131
	v_mul_f32_e32 v131, v133, v137
	v_rcp_f32_e32 v131, v131
	v_rndne_f32_e32 v136, v136
	v_min_f32_e32 v136, 0x437f0000, v136
	v_cvt_f16_f32_e32 v136, v136
	v_pk_mul_f32 v[132:133], v[132:133], v[130:131]
	v_add_f32_e32 v130, v11, v151
	v_pk_mul_f32 v[128:129], v[132:133], v[128:129]
	v_med3_f32 v130, v130, s6, v191
	v_cvt_pk_f16_f32 v132, v128, v129
	v_add_f32_e32 v129, v10, v150
	v_med3_f32 v129, v129, s6, v191
	v_mul_f32_e32 v129, 0xbfb8aa3b, v129
	v_exp_f32_e32 v129, v129
	v_mul_f32_e32 v128, v137, v131
	v_mul_f32_e32 v128, 0x437f0000, v128
	v_rndne_f32_e32 v131, v128
	v_add_f32_e32 v128, v14, v146
	v_add_f32_e32 v133, 1.0, v129
	v_add_f32_e32 v129, v15, v147
	v_med3_f32 v128, v128, s6, v191
	v_med3_f32 v129, v129, s6, v191
	v_mul_f32_e32 v128, 0xbfb8aa3b, v128
	v_mul_f32_e32 v129, 0xbfb8aa3b, v129
	v_exp_f32_e32 v128, v128
	v_exp_f32_e32 v129, v129
	v_mul_f32_e32 v130, 0xbfb8aa3b, v130
	v_exp_f32_e32 v137, v130
	v_min_f32_e32 v131, 0x437f0000, v131
	v_pk_add_f32 v[128:129], v[128:129], 1.0 op_sel_hi:[1,0]
	v_cvt_f16_f32_e32 v138, v131
	v_mul_f32_e32 v130, v128, v133
	v_rcp_f32_e32 v130, v130
	v_add_f32_e32 v137, 1.0, v137
	v_mul_f32_e32 v131, v133, v130
	v_mul_f32_e32 v133, 0x437f0000, v131
	v_mul_f32_e32 v131, v129, v137
	v_rcp_f32_e32 v131, v131
	v_rndne_f32_e32 v133, v133
	v_min_f32_e32 v133, 0x437f0000, v133
	v_cvt_f16_f32_e32 v133, v133
	v_mul_f32_e32 v137, v137, v131
	v_mul_f32_e32 v137, 0x437f0000, v137
	v_rndne_f32_e32 v137, v137
	v_min_f32_e32 v137, 0x437f0000, v137
	v_cvt_f16_f32_e32 v137, v137
	v_pk_mul_f32 v[128:129], v[128:129], v[130:131]
	s_nop 0
	v_pk_mul_f32 v[128:129], v[128:129], v[134:135]
	s_nop 0
	v_cvt_pk_f16_f32 v128, v128, v129
	v_bfi_b32 v131, s98, v137, v128
	v_bfi_b32 v129, s98, v138, v132
	v_pack_b32_f16 v130, v133, v128
	v_pack_b32_f16 v128, v136, v132
	ds_write_b128 v158, v[128:131] offset:28672
	v_cndmask_b32_e64 v128, v200, v156, s[4:5]
	v_and_b32_e32 v140, 7, v128
	v_ashrrev_i32_e32 v136, 3, v128
	v_lshlrev_b32_e32 v133, 1, v140
	v_lshl_add_u32 v132, v136, 8, v192
	v_bitop3_b32 v128, v133, v136, 15 bitop3:0x78
	v_lshl_or_b32 v128, v128, 4, v132
	s_waitcnt lgkmcnt(0)
	s_barrier
	ds_read_b128 v[128:131], v128
	v_and_b32_e32 v134, 15, v136
	v_bitop3_b32 v133, v133, v134, 1 bitop3:0x36
	v_lshl_or_b32 v132, v133, 4, v132
	ds_read_b128 v[132:135], v132
	s_waitcnt lgkmcnt(0)
	v_cvt_f32_f16_e32 v137, v128
	v_cvt_f32_f16_e32 v138, v129
	v_cvt_f32_f16_e32 v139, v130
	v_cvt_f32_f16_e32 v141, v131
	v_cvt_u32_f32_e32 v137, v137
	v_cvt_u32_f32_e32 v138, v138
	v_cvt_u32_f32_sdwa v139, v139 dst_sel:WORD_1 dst_unused:UNUSED_PAD src0_sel:DWORD
	v_cvt_u32_f32_sdwa v141, v141 dst_sel:BYTE_3 dst_unused:UNUSED_PAD src0_sel:DWORD
	v_and_b32_e32 v131, 0xffff0000, v131
	v_and_b32_e32 v142, 0xffff0000, v129
	v_lshl_or_b32 v129, v138, 8, v137
	v_or3_b32 v138, v129, v139, v141
	v_or_b32_sdwa v129, v131, v130 dst_sel:DWORD dst_unused:UNUSED_PAD src0_sel:DWORD src1_sel:WORD_1
	v_cvt_f32_f16_e32 v130, v132
	v_cvt_f32_f16_e32 v131, v133
	v_cvt_f32_f16_e32 v137, v134
	v_cvt_f32_f16_e32 v139, v135
	v_cvt_u32_f32_e32 v130, v130
	v_cvt_u32_f32_e32 v131, v131
	v_cvt_u32_f32_sdwa v137, v137 dst_sel:WORD_1 dst_unused:UNUSED_PAD src0_sel:DWORD
	v_cvt_u32_f32_sdwa v139, v139 dst_sel:BYTE_3 dst_unused:UNUSED_PAD src0_sel:DWORD
	v_and_b32_e32 v133, 0xffff0000, v133
	v_lshl_or_b32 v130, v131, 8, v130
	v_and_b32_e32 v135, 0xffff0000, v135
	v_or3_b32 v139, v130, v137, v139
	v_ashrrev_i32_e32 v137, 31, v136
	v_or_b32_sdwa v130, v133, v132 dst_sel:DWORD dst_unused:UNUSED_PAD src0_sel:DWORD src1_sel:WORD_1
	v_lshlrev_b64 v[132:133], 10, v[136:137]
	v_or_b32_sdwa v131, v135, v134 dst_sel:DWORD dst_unused:UNUSED_PAD src0_sel:DWORD src1_sel:WORD_1
	v_lshl_add_u64 v[132:133], s[12:13], 0, v[132:133]
	v_lshlrev_b32_e32 v134, 3, v140
	v_mov_b32_e32 v135, v164
	v_lshl_add_u64 v[132:133], v[132:133], 0, v[134:135]
	global_store_dwordx2 v[132:133], v[138:139], off
	v_lshlrev_b32_e32 v132, 4, v140
	v_or_b32_sdwa v128, v142, v128 dst_sel:DWORD dst_unused:UNUSED_PAD src0_sel:DWORD src1_sel:WORD_1
	v_lshl_or_b32 v132, v136, 11, v132
	buffer_store_dwordx4 v[128:131], v132, s[8:11], 0 offen sc1
	s_nop 1
	v_add_u32_e32 v128, 0x200, v156
	v_cndmask_b32_e64 v128, v128, v200, s[4:5]
	v_and_b32_e32 v140, 7, v128
	v_ashrrev_i32_e32 v136, 3, v128
	v_lshlrev_b32_e32 v132, 1, v140
	v_bitop3_b32 v128, v132, v136, 15 bitop3:0x78
	v_lshl_add_u32 v197, v136, 8, v192
	v_lshlrev_b32_e32 v199, 4, v128
	v_or_b32_e32 v128, v197, v199
	ds_read_b128 v[128:131], v128
	v_and_b32_e32 v133, 15, v136
	v_bitop3_b32 v132, v132, v133, 1 bitop3:0x36
	v_lshlrev_b32_e32 v198, 4, v132
	v_or_b32_e32 v132, v197, v198
	ds_read_b128 v[132:135], v132
	s_waitcnt lgkmcnt(1)
	v_cvt_f32_f16_e32 v137, v128
	v_cvt_f32_f16_e32 v138, v129
	v_cvt_f32_f16_e32 v139, v130
	v_cvt_f32_f16_e32 v141, v131
	v_cvt_u32_f32_e32 v137, v137
	v_cvt_u32_f32_e32 v138, v138
	v_cvt_u32_f32_sdwa v139, v139 dst_sel:WORD_1 dst_unused:UNUSED_PAD src0_sel:DWORD
	v_cvt_u32_f32_sdwa v141, v141 dst_sel:BYTE_3 dst_unused:UNUSED_PAD src0_sel:DWORD
	v_and_b32_e32 v131, 0xffff0000, v131
	v_and_b32_e32 v142, 0xffff0000, v129
	v_lshl_or_b32 v129, v138, 8, v137
	v_or3_b32 v138, v129, v139, v141
	v_or_b32_sdwa v129, v131, v130 dst_sel:DWORD dst_unused:UNUSED_PAD src0_sel:DWORD src1_sel:WORD_1
	s_waitcnt lgkmcnt(0)
	v_cvt_f32_f16_e32 v130, v132
	v_cvt_f32_f16_e32 v131, v133
	v_cvt_f32_f16_e32 v137, v134
	v_cvt_f32_f16_e32 v139, v135
	v_cvt_u32_f32_e32 v130, v130
	v_cvt_u32_f32_e32 v131, v131
	v_cvt_u32_f32_sdwa v137, v137 dst_sel:WORD_1 dst_unused:UNUSED_PAD src0_sel:DWORD
	v_cvt_u32_f32_sdwa v139, v139 dst_sel:BYTE_3 dst_unused:UNUSED_PAD src0_sel:DWORD
	v_and_b32_e32 v133, 0xffff0000, v133
	v_lshl_or_b32 v130, v131, 8, v130
	v_and_b32_e32 v135, 0xffff0000, v135
	v_or3_b32 v139, v130, v137, v139
	v_ashrrev_i32_e32 v137, 31, v136
	v_or_b32_sdwa v130, v133, v132 dst_sel:DWORD dst_unused:UNUSED_PAD src0_sel:DWORD src1_sel:WORD_1
	v_lshlrev_b64 v[132:133], 10, v[136:137]
	v_or_b32_sdwa v131, v135, v134 dst_sel:DWORD dst_unused:UNUSED_PAD src0_sel:DWORD src1_sel:WORD_1
	v_lshl_add_u64 v[132:133], s[12:13], 0, v[132:133]
	v_lshlrev_b32_e32 v134, 3, v140
	v_mov_b32_e32 v135, v164
	v_lshl_add_u64 v[150:151], v[132:133], 0, v[134:135]
	v_lshlrev_b32_e32 v132, 4, v140
	v_or_b32_sdwa v128, v142, v128 dst_sel:DWORD dst_unused:UNUSED_PAD src0_sel:DWORD src1_sel:WORD_1
	v_lshl_or_b32 v196, v136, 11, v132
	global_store_dwordx2 v[150:151], v[138:139], off
	buffer_store_dwordx4 v[128:131], v196, s[8:11], 0 offen sc1
	v_add_u32_e32 v132, 0x600, v156
	v_ashrrev_i32_e32 v142, 3, v132
	v_add_u32_e32 v128, 0x300, v156
	v_and_b32_e32 v129, 7, v157
	v_add_u32_e32 v130, 0x400, v156
	v_add_u32_e32 v131, 0x500, v156
	v_ashrrev_i32_e32 v148, 3, v128
	v_lshlrev_b32_e32 v160, 1, v129
	v_lshlrev_b32_e32 v140, 3, v129
	v_lshlrev_b32_e32 v159, 4, v129
	v_ashrrev_i32_e32 v146, 3, v130
	v_ashrrev_i32_e32 v144, 3, v131
	s_and_saveexec_b64 s[4:5], vcc
	s_xor_b64 s[4:5], exec, s[4:5]
	s_cbranch_execz .LBB0_459
	v_lshl_add_u32 v129, v148, 8, v192
	v_bitop3_b32 v128, v148, v160, 15 bitop3:0x6c
	v_lshl_or_b32 v130, v128, 4, v129
	v_or_b32_e32 v128, 1, v160
	v_bitop3_b32 v131, v148, v128, 15 bitop3:0x6c
	v_lshl_or_b32 v129, v131, 4, v129
	ds_read_b128 v[130:133], v130
	v_ashrrev_i32_e32 v149, 31, v148
	v_mov_b32_e32 v141, v164
	v_ashrrev_i32_e32 v147, 31, v146
	v_ashrrev_i32_e32 v145, 31, v144
	s_waitcnt lgkmcnt(0)
	v_and_b32_e32 v135, 0xffff0000, v131
	v_cvt_f32_f16_e32 v136, v130
	v_cvt_f32_f16_e32 v131, v131
	v_and_b32_e32 v134, 0xffff0000, v133
	v_cvt_f32_f16_e32 v137, v132
	v_cvt_f32_f16_e32 v133, v133
	v_cvt_u32_f32_e32 v136, v136
	v_cvt_u32_f32_e32 v131, v131
	v_cvt_u32_f32_sdwa v137, v137 dst_sel:WORD_1 dst_unused:UNUSED_PAD src0_sel:DWORD
	v_cvt_u32_f32_sdwa v133, v133 dst_sel:BYTE_3 dst_unused:UNUSED_PAD src0_sel:DWORD
	v_or_b32_sdwa v130, v135, v130 dst_sel:DWORD dst_unused:UNUSED_PAD src0_sel:DWORD src1_sel:WORD_1
	v_lshl_or_b32 v131, v131, 8, v136
	v_ashrrev_i32_e32 v143, 31, v142
	v_or3_b32 v136, v131, v137, v133
	v_or_b32_sdwa v131, v134, v132 dst_sel:DWORD dst_unused:UNUSED_PAD src0_sel:DWORD src1_sel:WORD_1
	ds_read_b128 v[132:135], v129
	s_waitcnt lgkmcnt(0)
	v_and_b32_e32 v138, 0xffff0000, v133
	v_cvt_f32_f16_e32 v137, v132
	v_cvt_f32_f16_e32 v133, v133
	v_and_b32_e32 v129, 0xffff0000, v135
	v_cvt_f32_f16_e32 v139, v134
	v_cvt_f32_f16_e32 v135, v135
	v_cvt_u32_f32_e32 v137, v137
	v_cvt_u32_f32_e32 v133, v133
	v_cvt_u32_f32_sdwa v139, v139 dst_sel:WORD_1 dst_unused:UNUSED_PAD src0_sel:DWORD
	v_cvt_u32_f32_sdwa v135, v135 dst_sel:BYTE_3 dst_unused:UNUSED_PAD src0_sel:DWORD
	v_or_b32_sdwa v132, v138, v132 dst_sel:DWORD dst_unused:UNUSED_PAD src0_sel:DWORD src1_sel:WORD_1
	v_lshl_or_b32 v133, v133, 8, v137
	v_or3_b32 v137, v133, v139, v135
	v_or_b32_sdwa v133, v129, v134 dst_sel:DWORD dst_unused:UNUSED_PAD src0_sel:DWORD src1_sel:WORD_1
	v_lshlrev_b64 v[134:135], 10, v[148:149]
	v_lshl_add_u64 v[134:135], s[12:13], 0, v[134:135]
	v_lshl_add_u64 v[134:135], v[134:135], 0, v[140:141]
	v_lshl_or_b32 v129, v148, 11, v159
	global_store_dwordx2 v[134:135], v[136:137], off
	buffer_store_dwordx4 v[130:133], v129, s[8:11], 0 offen sc1
	v_lshl_add_u32 v129, v146, 8, v192
	s_nop 0
	v_bitop3_b32 v130, v146, v160, 15 bitop3:0x6c
	v_lshl_or_b32 v130, v130, 4, v129
	v_bitop3_b32 v131, v146, v128, 15 bitop3:0x6c
	v_lshl_or_b32 v129, v131, 4, v129
	ds_read_b128 v[130:133], v130
	s_waitcnt lgkmcnt(0)
	v_and_b32_e32 v135, 0xffff0000, v131
	v_cvt_f32_f16_e32 v136, v130
	v_cvt_f32_f16_e32 v131, v131
	v_and_b32_e32 v134, 0xffff0000, v133
	v_cvt_f32_f16_e32 v137, v132
	v_cvt_f32_f16_e32 v133, v133
	v_cvt_u32_f32_e32 v136, v136
	v_cvt_u32_f32_e32 v131, v131
	v_cvt_u32_f32_sdwa v137, v137 dst_sel:WORD_1 dst_unused:UNUSED_PAD src0_sel:DWORD
	v_cvt_u32_f32_sdwa v133, v133 dst_sel:BYTE_3 dst_unused:UNUSED_PAD src0_sel:DWORD
	v_or_b32_sdwa v130, v135, v130 dst_sel:DWORD dst_unused:UNUSED_PAD src0_sel:DWORD src1_sel:WORD_1
	v_lshl_or_b32 v131, v131, 8, v136
	v_or3_b32 v136, v131, v137, v133
	v_or_b32_sdwa v131, v134, v132 dst_sel:DWORD dst_unused:UNUSED_PAD src0_sel:DWORD src1_sel:WORD_1
	ds_read_b128 v[132:135], v129
	s_waitcnt lgkmcnt(0)
	v_and_b32_e32 v138, 0xffff0000, v133
	v_cvt_f32_f16_e32 v137, v132
	v_cvt_f32_f16_e32 v133, v133
	v_and_b32_e32 v129, 0xffff0000, v135
	v_cvt_f32_f16_e32 v139, v134
	v_cvt_f32_f16_e32 v135, v135
	v_cvt_u32_f32_e32 v137, v137
	v_cvt_u32_f32_e32 v133, v133
	v_cvt_u32_f32_sdwa v139, v139 dst_sel:WORD_1 dst_unused:UNUSED_PAD src0_sel:DWORD
	v_cvt_u32_f32_sdwa v135, v135 dst_sel:BYTE_3 dst_unused:UNUSED_PAD src0_sel:DWORD
	v_or_b32_sdwa v132, v138, v132 dst_sel:DWORD dst_unused:UNUSED_PAD src0_sel:DWORD src1_sel:WORD_1
	v_lshl_or_b32 v133, v133, 8, v137
	v_or3_b32 v137, v133, v139, v135
	v_or_b32_sdwa v133, v129, v134 dst_sel:DWORD dst_unused:UNUSED_PAD src0_sel:DWORD src1_sel:WORD_1
	v_lshlrev_b64 v[134:135], 10, v[146:147]
	v_lshl_add_u64 v[134:135], s[12:13], 0, v[134:135]
	v_lshl_add_u64 v[134:135], v[134:135], 0, v[140:141]
	v_lshl_or_b32 v129, v146, 11, v159
	global_store_dwordx2 v[134:135], v[136:137], off
	buffer_store_dwordx4 v[130:133], v129, s[8:11], 0 offen sc1
	v_lshl_add_u32 v129, v144, 8, v192
	s_nop 0
	v_bitop3_b32 v130, v144, v160, 15 bitop3:0x6c
	v_lshl_or_b32 v130, v130, 4, v129
	v_bitop3_b32 v131, v144, v128, 15 bitop3:0x6c
	v_lshl_or_b32 v129, v131, 4, v129
	ds_read_b128 v[130:133], v130
	v_bitop3_b32 v128, v142, v128, 15 bitop3:0x6c
	s_waitcnt lgkmcnt(0)
	v_and_b32_e32 v135, 0xffff0000, v131
	v_cvt_f32_f16_e32 v136, v130
	v_cvt_f32_f16_e32 v131, v131
	v_and_b32_e32 v134, 0xffff0000, v133
	v_cvt_f32_f16_e32 v137, v132
	v_cvt_f32_f16_e32 v133, v133
	v_cvt_u32_f32_e32 v136, v136
	v_cvt_u32_f32_e32 v131, v131
	v_cvt_u32_f32_sdwa v137, v137 dst_sel:WORD_1 dst_unused:UNUSED_PAD src0_sel:DWORD
	v_cvt_u32_f32_sdwa v133, v133 dst_sel:BYTE_3 dst_unused:UNUSED_PAD src0_sel:DWORD
	v_or_b32_sdwa v130, v135, v130 dst_sel:DWORD dst_unused:UNUSED_PAD src0_sel:DWORD src1_sel:WORD_1
	v_lshl_or_b32 v131, v131, 8, v136
	v_or3_b32 v136, v131, v137, v133
	v_or_b32_sdwa v131, v134, v132 dst_sel:DWORD dst_unused:UNUSED_PAD src0_sel:DWORD src1_sel:WORD_1
	ds_read_b128 v[132:135], v129
	s_waitcnt lgkmcnt(0)
	v_and_b32_e32 v138, 0xffff0000, v133
	v_cvt_f32_f16_e32 v137, v132
	v_cvt_f32_f16_e32 v133, v133
	v_and_b32_e32 v129, 0xffff0000, v135
	v_cvt_f32_f16_e32 v139, v134
	v_cvt_f32_f16_e32 v135, v135
	v_cvt_u32_f32_e32 v137, v137
	v_cvt_u32_f32_e32 v133, v133
	v_cvt_u32_f32_sdwa v139, v139 dst_sel:WORD_1 dst_unused:UNUSED_PAD src0_sel:DWORD
	v_cvt_u32_f32_sdwa v135, v135 dst_sel:BYTE_3 dst_unused:UNUSED_PAD src0_sel:DWORD
	v_or_b32_sdwa v132, v138, v132 dst_sel:DWORD dst_unused:UNUSED_PAD src0_sel:DWORD src1_sel:WORD_1
	v_lshl_or_b32 v133, v133, 8, v137
	v_or3_b32 v137, v133, v139, v135
	v_or_b32_sdwa v133, v129, v134 dst_sel:DWORD dst_unused:UNUSED_PAD src0_sel:DWORD src1_sel:WORD_1
	v_lshlrev_b64 v[134:135], 10, v[144:145]
	v_lshl_add_u64 v[134:135], s[12:13], 0, v[134:135]
	v_lshl_add_u64 v[134:135], v[134:135], 0, v[140:141]
	v_lshl_or_b32 v129, v144, 11, v159
	global_store_dwordx2 v[134:135], v[136:137], off
	buffer_store_dwordx4 v[130:133], v129, s[8:11], 0 offen sc1
	v_lshl_add_u32 v129, v142, 8, v192
	s_nop 0
	v_bitop3_b32 v130, v142, v160, 15 bitop3:0x6c
	v_lshl_or_b32 v130, v130, 4, v129
	v_lshl_or_b32 v132, v128, 4, v129
	ds_read_b128 v[128:131], v130
	s_waitcnt lgkmcnt(0)
	v_and_b32_e32 v135, 0xffff0000, v129
	v_cvt_f32_f16_e32 v134, v128
	v_cvt_f32_f16_e32 v129, v129
	v_and_b32_e32 v133, 0xffff0000, v131
	v_cvt_f32_f16_e32 v136, v130
	v_cvt_f32_f16_e32 v131, v131
	v_cvt_u32_f32_e32 v134, v134
	v_cvt_u32_f32_e32 v129, v129
	v_cvt_u32_f32_sdwa v136, v136 dst_sel:WORD_1 dst_unused:UNUSED_PAD src0_sel:DWORD
	v_cvt_u32_f32_sdwa v131, v131 dst_sel:BYTE_3 dst_unused:UNUSED_PAD src0_sel:DWORD
	v_or_b32_sdwa v128, v135, v128 dst_sel:DWORD dst_unused:UNUSED_PAD src0_sel:DWORD src1_sel:WORD_1
	v_lshl_or_b32 v129, v129, 8, v134
	v_or3_b32 v134, v129, v136, v131
	v_or_b32_sdwa v129, v133, v130 dst_sel:DWORD dst_unused:UNUSED_PAD src0_sel:DWORD src1_sel:WORD_1
	ds_read_b128 v[130:133], v132
	s_waitcnt lgkmcnt(0)
	v_and_b32_e32 v137, 0xffff0000, v131
	v_cvt_f32_f16_e32 v135, v130
	v_cvt_f32_f16_e32 v131, v131
	v_and_b32_e32 v136, 0xffff0000, v133
	v_cvt_f32_f16_e32 v138, v132
	v_cvt_f32_f16_e32 v133, v133
	v_cvt_u32_f32_e32 v135, v135
	v_cvt_u32_f32_e32 v131, v131
	v_cvt_u32_f32_sdwa v138, v138 dst_sel:WORD_1 dst_unused:UNUSED_PAD src0_sel:DWORD
	v_cvt_u32_f32_sdwa v133, v133 dst_sel:BYTE_3 dst_unused:UNUSED_PAD src0_sel:DWORD
	v_or_b32_sdwa v130, v137, v130 dst_sel:DWORD dst_unused:UNUSED_PAD src0_sel:DWORD src1_sel:WORD_1
	v_lshl_or_b32 v131, v131, 8, v135
	v_or3_b32 v135, v131, v138, v133
	v_or_b32_sdwa v131, v136, v132 dst_sel:DWORD dst_unused:UNUSED_PAD src0_sel:DWORD src1_sel:WORD_1
	v_lshlrev_b64 v[132:133], 10, v[142:143]
	v_lshl_add_u64 v[132:133], s[12:13], 0, v[132:133]
	v_lshl_add_u64 v[132:133], v[132:133], 0, v[140:141]
	global_store_dwordx2 v[132:133], v[134:135], off
	v_lshl_or_b32 v132, v142, 11, v159
	buffer_store_dwordx4 v[128:131], v132, s[8:11], 0 offen sc1
.LBB0_459:
	s_or_saveexec_b64 s[16:17], s[4:5]
	s_nop 0
	v_lshlrev_b32_e32 v128, 2, v157
	v_and_b32_e32 v143, 12, v128
	v_lshlrev_b32_e32 v128, 4, v156
	v_bitop3_b32 v136, v201, 63, v157 bitop3:0xc8
	s_movk_i32 s4, 0xffc0
	v_and_b32_e32 v138, 0xfffffc00, v128
	v_bitop3_b32 v137, v201, s4, v157 bitop3:0xc8
	v_bfe_u32 v139, v156, 2, 4
	v_add_u32_e32 v141, 0x80000, v138
	v_lshlrev_b32_e32 v145, 2, v136
	s_xor_b64 exec, exec, s[16:17]
	s_cbranch_execz .LBB0_463
	v_mov_b32_e32 v128, v246
	s_mov_b32 s4, 0x3f2aaaab
	s_cmp_eq_u32 s45, 0
	s_mov_b32 s18, 0
	s_mov_b32 s19, 56
	v_mul_f32_e32 v128, 0xbfb8aa3b, v128
	v_exp_f32_e32 v130, v128
	s_nop 0
	v_add_f32_e32 v131, 1.0, v130
	v_add_f32_e32 v128, -1.0, v131
	v_sub_f32_e32 v129, v128, v131
	v_add_f32_e32 v129, 1.0, v129
	v_sub_f32_e32 v128, v130, v128
	v_add_f32_e32 v132, v128, v129
	v_frexp_mant_f32_e32 v128, v131
	v_cmp_gt_f32_e64 s[4:5], s4, v128
	v_cvt_f64_f32_e32 v[128:129], v131
	v_frexp_exp_i32_f64_e32 v128, v[128:129]
	v_subbrev_co_u32_e64 v128, s[4:5], 0, v128, s[4:5]
	v_sub_u32_e32 v129, 0, v128
	v_ldexp_f32 v131, v131, v129
	v_ldexp_f32 v129, v132, v129
	v_add_f32_e32 v132, -1.0, v131
	v_add_f32_e32 v133, 1.0, v132
	v_sub_f32_e32 v133, v131, v133
	v_add_f32_e32 v133, v129, v133
	v_add_f32_e32 v134, v132, v133
	v_sub_f32_e32 v132, v134, v132
	v_sub_f32_e32 v132, v133, v132
	v_add_f32_e32 v133, 1.0, v131
	v_add_f32_e32 v135, -1.0, v133
	v_sub_f32_e32 v131, v131, v135
	v_add_f32_e32 v129, v129, v131
	v_add_f32_e32 v131, v133, v129
	v_sub_f32_e32 v133, v131, v133
	v_sub_f32_e32 v129, v129, v133
	v_rcp_f32_e32 v133, v131
	v_cvt_f32_i32_e32 v128, v128
	s_mov_b32 s4, 0x3f317218
	v_mul_f32_e32 v135, v134, v133
	v_mul_f32_e32 v147, v131, v135
	v_fma_f32 v149, v135, v131, -v147
	v_fmac_f32_e32 v149, v135, v129
	v_add_f32_e32 v157, v147, v149
	v_sub_f32_e32 v200, v134, v157
	v_sub_f32_e32 v134, v134, v200
	v_sub_f32_e32 v147, v157, v147
	v_sub_f32_e32 v134, v134, v157
	v_add_f32_e32 v132, v132, v134
	v_sub_f32_e32 v134, v147, v149
	v_add_f32_e32 v132, v134, v132
	v_add_f32_e32 v134, v200, v132
	v_mul_f32_e32 v147, v133, v134
	v_mul_f32_e32 v149, v131, v147
	v_fma_f32 v131, v147, v131, -v149
	v_fmac_f32_e32 v131, v147, v129
	v_sub_f32_e32 v129, v200, v134
	v_add_f32_e32 v129, v132, v129
	v_add_f32_e32 v132, v149, v131
	v_sub_f32_e32 v157, v134, v132
	v_sub_f32_e32 v134, v134, v157
	v_sub_f32_e32 v149, v132, v149
	v_sub_f32_e32 v132, v134, v132
	v_add_f32_e32 v129, v129, v132
	v_sub_f32_e32 v131, v149, v131
	v_add_f32_e32 v129, v131, v129
	v_add_f32_e32 v131, v135, v147
	v_add_f32_e32 v129, v157, v129
	v_sub_f32_e32 v132, v131, v135
	v_mul_f32_e32 v129, v133, v129
	v_sub_f32_e32 v132, v147, v132
	v_add_f32_e32 v129, v132, v129
	v_mul_f32_e32 v135, 0x3f317218, v128
	v_add_f32_e32 v132, v131, v129
	v_fma_f32 v147, v128, s4, -v135
	v_mul_f32_e32 v133, v132, v132
	v_fmac_f32_e32 v147, 0xb102e308, v128
	v_sub_f32_e32 v128, v132, v131
	v_fmamk_f32 v134, v133, 0x3e9b6dac, v185
	v_sub_f32_e32 v128, v129, v128
	v_add_f32_e32 v129, v135, v147
	v_fmaak_f32 v134, v133, v134, 0x3f2aaada
	v_sub_f32_e32 v131, v129, v135
	v_ldexp_f32 v135, v132, 1
	v_mul_f32_e32 v132, v132, v133
	v_mul_f32_e32 v132, v132, v134
	v_add_f32_e32 v133, v135, v132
	v_sub_f32_e32 v134, v133, v135
	v_ldexp_f32 v128, v128, 1
	v_sub_f32_e32 v132, v132, v134
	v_add_f32_e32 v128, v128, v132
	v_add_f32_e32 v132, v133, v128
	v_sub_f32_e32 v133, v132, v133
	v_sub_f32_e32 v128, v128, v133
	v_add_f32_e32 v133, v129, v132
	v_sub_f32_e32 v134, v133, v129
	v_sub_f32_e32 v135, v133, v134
	v_sub_f32_e32 v131, v147, v131
	v_sub_f32_e32 v129, v129, v135
	v_sub_f32_e32 v132, v132, v134
	v_add_f32_e32 v129, v132, v129
	v_add_f32_e32 v132, v131, v128
	v_sub_f32_e32 v134, v132, v131
	v_sub_f32_e32 v135, v132, v134
	v_sub_f32_e32 v131, v131, v135
	v_sub_f32_e32 v128, v128, v134
	v_add_f32_e32 v129, v132, v129
	v_add_f32_e32 v128, v128, v131
	v_add_f32_e32 v131, v133, v129
	v_sub_f32_e32 v132, v131, v133
	v_sub_f32_e32 v129, v129, v132
	v_add_f32_e32 v128, v128, v129
	s_mov_b32 s4, 0x7f800000
	v_add_f32_e32 v128, v131, v128
	v_cmp_neq_f32_e64 s[4:5], s4, v130
	s_nop 1
	v_cndmask_b32_e64 v128, v187, v128, s[4:5]
	v_cmp_ngt_f32_e64 s[4:5], -1.0, v130
	s_nop 1
	v_cndmask_b32_e64 v128, v188, v128, s[4:5]
	v_cmp_neq_f32_e64 s[4:5], -1.0, v130
	s_nop 1
	v_cndmask_b32_e64 v128, v189, v128, s[4:5]
	s_mov_b32 s4, 0x33800000
	v_cmp_lt_f32_e64 s[4:5], |v130|, s4
	s_nop 1
	v_cndmask_b32_e64 v128, v128, v130, s[4:5]
	v_mul_f32_e32 v128, 0xc1000000, v128
	v_mul_f32_e32 v130, 0x3b808081, v128
	v_mov_b32_e32 v128, 0
	s_cselect_b64 s[4:5], -1, 0
	v_mov_b32_e32 v129, v128
	s_cmp_eq_u32 s45, 0
	s_cselect_b32 s34, 0, 0x3ff0
	v_lshlrev_b32_e32 v131, 8, v137
	v_lshl_or_b32 v131, v139, 4, v131
	v_or_b32_e32 v131, v131, v143
	v_or_b32_e32 v131, 0x10000, v131
	v_xor_b32_e32 v131, s34, v131
	s_mov_b32 s34, 0
	ds_read_b32 v226, v131
	v_xor_b32_e32 v243, 0x110, v131
	ds_read_b32 v227, v243
	v_xor_b32_e32 v244, 0x220, v131
	ds_read_b32 v228, v244
	v_xor_b32_e32 v245, 0x330, v131
	ds_read_b32 v229, v245

.LBB0_465:
	s_andn2_saveexec_b64 s[4:5], s[4:5]
	s_cbranch_execz .LBB0_469
	v_mov_b32_e32 v128, v247
	s_mov_b32 s8, 0x3f2aaaab
	s_cmp_eq_u32 s45, 0
	s_mov_b32 s16, 0
	s_mov_b32 s17, 56
	v_mul_f32_e32 v128, 0xbfb8aa3b, v128
	v_exp_f32_e32 v130, v128
	s_nop 0
	v_add_f32_e32 v131, 1.0, v130
	v_add_f32_e32 v128, -1.0, v131
	v_sub_f32_e32 v129, v128, v131
	v_add_f32_e32 v129, 1.0, v129
	v_sub_f32_e32 v128, v130, v128
	v_add_f32_e32 v132, v128, v129
	v_frexp_mant_f32_e32 v128, v131
	v_cmp_gt_f32_e32 vcc, s8, v128
	v_cvt_f64_f32_e32 v[128:129], v131
	v_frexp_exp_i32_f64_e32 v128, v[128:129]
	v_subbrev_co_u32_e32 v128, vcc, 0, v128, vcc
	v_sub_u32_e32 v129, 0, v128
	v_ldexp_f32 v131, v131, v129
	v_ldexp_f32 v129, v132, v129
	v_add_f32_e32 v132, -1.0, v131
	v_add_f32_e32 v133, 1.0, v132
	v_sub_f32_e32 v133, v131, v133
	v_add_f32_e32 v133, v129, v133
	v_add_f32_e32 v134, v132, v133
	v_sub_f32_e32 v132, v134, v132
	v_sub_f32_e32 v132, v133, v132
	v_add_f32_e32 v133, 1.0, v131
	v_add_f32_e32 v135, -1.0, v133
	v_sub_f32_e32 v131, v131, v135
	v_add_f32_e32 v129, v129, v131
	v_add_f32_e32 v131, v133, v129
	v_sub_f32_e32 v133, v131, v133
	v_sub_f32_e32 v129, v129, v133
	v_rcp_f32_e32 v133, v131
	v_cvt_f32_i32_e32 v128, v128
	s_mov_b32 s8, 0x3f317218
	v_mul_f32_e32 v135, v134, v133
	v_mul_f32_e32 v140, v131, v135
	v_fma_f32 v142, v135, v131, -v140
	v_fmac_f32_e32 v142, v135, v129
	v_add_f32_e32 v144, v140, v142
	v_sub_f32_e32 v145, v134, v144
	v_sub_f32_e32 v134, v134, v145
	v_sub_f32_e32 v140, v144, v140
	v_sub_f32_e32 v134, v134, v144
	v_add_f32_e32 v132, v132, v134
	v_sub_f32_e32 v134, v140, v142
	v_add_f32_e32 v132, v134, v132
	v_add_f32_e32 v134, v145, v132
	v_mul_f32_e32 v140, v133, v134
	v_mul_f32_e32 v142, v131, v140
	v_fma_f32 v131, v140, v131, -v142
	v_fmac_f32_e32 v131, v140, v129
	v_sub_f32_e32 v129, v145, v134
	v_add_f32_e32 v129, v132, v129
	v_add_f32_e32 v132, v142, v131
	v_sub_f32_e32 v144, v134, v132
	v_sub_f32_e32 v134, v134, v144
	v_sub_f32_e32 v142, v132, v142
	v_sub_f32_e32 v132, v134, v132
	v_add_f32_e32 v129, v129, v132
	v_sub_f32_e32 v131, v142, v131
	v_add_f32_e32 v129, v131, v129
	v_add_f32_e32 v131, v135, v140
	v_add_f32_e32 v129, v144, v129
	v_sub_f32_e32 v132, v131, v135
	v_mul_f32_e32 v129, v133, v129
	v_sub_f32_e32 v132, v140, v132
	v_add_f32_e32 v129, v132, v129
	v_mul_f32_e32 v135, 0x3f317218, v128
	v_add_f32_e32 v132, v131, v129
	v_fma_f32 v140, v128, s8, -v135
	v_mul_f32_e32 v133, v132, v132
	v_fmac_f32_e32 v140, 0xb102e308, v128
	v_sub_f32_e32 v128, v132, v131
	v_fmamk_f32 v134, v133, 0x3e9b6dac, v185
	v_sub_f32_e32 v128, v129, v128
	v_add_f32_e32 v129, v135, v140
	v_fmaak_f32 v134, v133, v134, 0x3f2aaada
	v_sub_f32_e32 v131, v129, v135
	v_ldexp_f32 v135, v132, 1
	v_mul_f32_e32 v132, v132, v133
	v_mul_f32_e32 v132, v132, v134
	v_add_f32_e32 v133, v135, v132
	v_sub_f32_e32 v134, v133, v135
	v_ldexp_f32 v128, v128, 1
	v_sub_f32_e32 v132, v132, v134
	v_add_f32_e32 v128, v128, v132
	v_add_f32_e32 v132, v133, v128
	v_sub_f32_e32 v133, v132, v133
	v_sub_f32_e32 v128, v128, v133
	v_add_f32_e32 v133, v129, v132
	v_sub_f32_e32 v134, v133, v129
	v_sub_f32_e32 v135, v133, v134
	v_sub_f32_e32 v131, v140, v131
	v_sub_f32_e32 v129, v129, v135
	v_sub_f32_e32 v132, v132, v134
	v_add_f32_e32 v129, v132, v129
	v_add_f32_e32 v132, v131, v128
	v_sub_f32_e32 v134, v132, v131
	v_sub_f32_e32 v135, v132, v134
	v_sub_f32_e32 v131, v131, v135
	v_sub_f32_e32 v128, v128, v134
	v_add_f32_e32 v129, v132, v129
	v_add_f32_e32 v128, v128, v131
	v_add_f32_e32 v131, v133, v129
	v_sub_f32_e32 v132, v131, v133
	v_sub_f32_e32 v129, v129, v132
	v_add_f32_e32 v128, v128, v129
	s_mov_b32 s8, 0x7f800000
	v_add_f32_e32 v128, v131, v128
	v_cmp_neq_f32_e32 vcc, s8, v130
	s_mov_b32 s8, 0x33800000
	s_nop 0
	v_cndmask_b32_e32 v128, v187, v128, vcc
	v_cmp_ngt_f32_e32 vcc, -1.0, v130
	s_nop 1
	v_cndmask_b32_e32 v128, v188, v128, vcc
	v_cmp_neq_f32_e32 vcc, -1.0, v130
	s_nop 1
	v_cndmask_b32_e32 v128, v189, v128, vcc
	v_cmp_lt_f32_e64 vcc, |v130|, s8
	s_cselect_b64 s[8:9], -1, 0
	s_nop 0
	v_cndmask_b32_e32 v128, v128, v130, vcc
	v_mul_f32_e32 v128, 0xc1000000, v128
	v_mul_f32_e32 v130, 0x3b808081, v128
	v_mov_b32_e32 v128, 0
	v_mov_b32_e32 v129, v128
	s_cmp_eq_u32 s45, 0
	s_cselect_b32 s34, 0, 0x3ff0
	v_lshlrev_b32_e32 v131, 8, v137
	v_lshl_or_b32 v131, v139, 4, v131
	v_or_b32_e32 v131, v131, v143
	v_or_b32_e32 v131, 0x10000, v131
	v_xor_b32_e32 v131, s34, v131
	s_mov_b32 s34, 0
	ds_read_b32 v226, v131
	v_xor_b32_e32 v243, 0x110, v131
	ds_read_b32 v227, v243
	v_xor_b32_e32 v244, 0x220, v131
	ds_read_b32 v228, v244
	v_xor_b32_e32 v245, 0x330, v131
	ds_read_b32 v229, v245

; __global__ void __launch_bounds__(512) fwd_megakernel(Params p_unused) {
;   cg::grid_group grid = cg::this_grid();
;   KP pp = (KP)__builtin_amdgcn_kernarg_segment_ptr();
;   grid.sync();
;     ...
; #pragma clang loop unroll(disable)
;   for (int step = 0; step < DEPTH * NCHUNK * 10; ++step) {
;     const int lc = step / 10, phi = step - lc * 10, ph = phi < 4 ? phi : phi + 1, l = lc >> 2, c = lc & 3;
;     if (ph == 0 && c > 0) continue;
;     switch (ph) {
;       case 0: if (l > 0) phase_resid(pp, l - 1, NCHUNK - 1); phase_convert(pp, l); rows_mem(pp, l); phase_norm(pp, l, 0); break;
;       case 2: phase2(pp, l, c); break;
;       case 4: phase4a(pp); break;
;       case 5: phase4b(pp, c); break;
;       case 6: phase4c(pp, l); break;
;       case 8: phase6(pp, l, c); break;
;       default: break;
;     }
;     const int nt = gemm_ntiles(ph, c);
;     { int v = blockIdx.x;
;       TileDesc d, dn;
;       bool pend = true;
;       if (v < nt) { make_desc(pp, ph, l, c, v, d); __syncthreads(); gemm_prefetch(d); }
;       if (ph == 2 && c > 0) phase_resid(pp, l, c - 1);
;       if (ph == 10 && c + 1 < NCHUNK) phase_norm(pp, l, c + 1);
; #pragma clang loop unroll(disable)
;       while (v < nt) {
;         const int vn = v + gridDim.x; const bool hn = vn < nt;
;         if (hn) make_desc(pp, ph, l, c, vn, dn); else dn = d;
;         gemm_tile(d, dn, hn, pend);
;         pend = (d.kind == EPI_GATE);
;         d = dn; v = vn; } }
;     xcd_barrier(xb);
;   }
;   phase_final(pp);
; }
	.amdhsa_kernel _Z14fwd_megakernel6Params
		.amdhsa_group_segment_fixed_size 139264
		.amdhsa_private_segment_fixed_size 0
		.amdhsa_kernarg_size 456
		.amdhsa_user_sgpr_count 2
		.amdhsa_user_sgpr_dispatch_ptr 0
		.amdhsa_user_sgpr_queue_ptr 0
		.amdhsa_user_sgpr_kernarg_segment_ptr 1
		.amdhsa_user_sgpr_dispatch_id 0
		.amdhsa_user_sgpr_kernarg_preload_length 0
		.amdhsa_user_sgpr_kernarg_preload_offset 0
		.amdhsa_user_sgpr_private_segment_size 0
		.amdhsa_uses_dynamic_stack 0
		.amdhsa_enable_private_segment 0
		.amdhsa_system_sgpr_workgroup_id_x 1
		.amdhsa_system_sgpr_workgroup_id_y 0
		.amdhsa_system_sgpr_workgroup_id_z 0
		.amdhsa_system_sgpr_workgroup_info 0
		.amdhsa_system_vgpr_workitem_id 2
		.amdhsa_next_free_vgpr 248
		.amdhsa_next_free_sgpr 100
		.amdhsa_accum_offset 248
		.amdhsa_reserve_vcc 1
		.amdhsa_float_round_mode_32 0
		.amdhsa_float_round_mode_16_64 0
		.amdhsa_float_denorm_mode_32 3
		.amdhsa_float_denorm_mode_16_64 3
		.amdhsa_dx10_clamp 1
		.amdhsa_ieee_mode 1
		.amdhsa_fp16_overflow 0
		.amdhsa_tg_split 0
		.amdhsa_exception_fp_ieee_invalid_op 0
		.amdhsa_exception_fp_denorm_src 0
		.amdhsa_exception_fp_ieee_div_zero 0
		.amdhsa_exception_fp_ieee_overflow 0
		.amdhsa_exception_fp_ieee_underflow 0
		.amdhsa_exception_fp_ieee_inexact 0
		.amdhsa_exception_int_div_zero 0
	.end_amdhsa_kernel

; __global__ void __launch_bounds__(512) fwd_megakernel(Params p_unused) {
;   cg::grid_group grid = cg::this_grid();
;   KP pp = (KP)__builtin_amdgcn_kernarg_segment_ptr();
;   grid.sync();
;     ...
; #pragma clang loop unroll(disable)
;   for (int step = 0; step < DEPTH * NCHUNK * 10; ++step) {
;     const int lc = step / 10, phi = step - lc * 10, ph = phi < 4 ? phi : phi + 1, l = lc >> 2, c = lc & 3;
;     if (ph == 0 && c > 0) continue;
;     switch (ph) {
;       case 0: if (l > 0) phase_resid(pp, l - 1, NCHUNK - 1); phase_convert(pp, l); rows_mem(pp, l); phase_norm(pp, l, 0); break;
;       case 2: phase2(pp, l, c); break;
;       case 4: phase4a(pp); break;
;       case 5: phase4b(pp, c); break;
;       case 6: phase4c(pp, l); break;
;       case 8: phase6(pp, l, c); break;
;       default: break;
;     }
;     const int nt = gemm_ntiles(ph, c);
;     { int v = blockIdx.x;
;       TileDesc d, dn;
;       bool pend = true;
;       if (v < nt) { make_desc(pp, ph, l, c, v, d); __syncthreads(); gemm_prefetch(d); }
;       if (ph == 2 && c > 0) phase_resid(pp, l, c - 1);
;       if (ph == 10 && c + 1 < NCHUNK) phase_norm(pp, l, c + 1);
; #pragma clang loop unroll(disable)
;       while (v < nt) {
;         const int vn = v + gridDim.x; const bool hn = vn < nt;
;         if (hn) make_desc(pp, ph, l, c, vn, dn); else dn = d;
;         gemm_tile(d, dn, hn, pend);
;         pend = (d.kind == EPI_GATE);
;         d = dn; v = vn; } }
;     xcd_barrier(xb);
;   }
;   phase_final(pp);
; }
amdhsa.kernels:
  - .agpr_count:     0
    .args:
      - .offset:         0
        .size:           200
        .value_kind:     by_value
      - .offset:         200
        .size:           4
        .value_kind:     hidden_block_count_x
      - .offset:         204
        .size:           4
        .value_kind:     hidden_block_count_y
      - .offset:         208
        .size:           4
        .value_kind:     hidden_block_count_z
      - .offset:         212
        .size:           2
        .value_kind:     hidden_group_size_x
      - .offset:         214
        .size:           2
        .value_kind:     hidden_group_size_y
      - .offset:         216
        .size:           2
        .value_kind:     hidden_group_size_z
      - .offset:         218
        .size:           2
        .value_kind:     hidden_remainder_x
      - .offset:         220
        .size:           2
        .value_kind:     hidden_remainder_y
      - .offset:         222
        .size:           2
        .value_kind:     hidden_remainder_z
      - .offset:         240
        .size:           8
        .value_kind:     hidden_global_offset_x
      - .offset:         248
        .size:           8
        .value_kind:     hidden_global_offset_y
      - .offset:         256
        .size:           8
        .value_kind:     hidden_global_offset_z
      - .offset:         264
        .size:           2
        .value_kind:     hidden_grid_dims
      - .offset:         288
        .size:           8
        .value_kind:     hidden_multigrid_sync_arg
    .group_segment_fixed_size: 139264
    .kernarg_segment_align: 8
    .kernarg_segment_size: 456
    .language:       OpenCL C
    .language_version:
      - 2
      - 0
    .max_flat_workgroup_size: 512
    .name:           _Z14fwd_megakernel6Params
    .private_segment_fixed_size: 0
    .sgpr_count:     106
    .sgpr_spill_count: 125
    .symbol:         _Z14fwd_megakernel6Params.kd
    .uniform_work_group_size: 1
    .uses_dynamic_stack: false
    .vgpr_count:     248
    .vgpr_spill_count: 0
    .wavefront_size: 64
